# LDS-DMA attention loop: S-chain MFMAs separated by PV MFMAs (S,PV,PV,S,PV,PV) in each 16-key step
# baseline (speedup 1.0000x reference)
.Lattn_nf_loop:
	ds_read_b128 v[98:101], v82 offset:0
	ds_read_b128 v[102:105], v83 offset:0
	ds_read_b128 v[106:109], v84 offset:0
	ds_read_b128 v[110:113], v85 offset:0
	s_and_b32 s10, s15, 1
	s_xor_b32 s10, s10, 1
	s_lshl_b32 s10, s10, 15
	s_add_i32 s10, s10, s11
	s_add_i32 s6, s10, 0x10000
	s_waitcnt lgkmcnt(3)
	v_mfma_f32_32x32x16_bf16 v[138:153], v[98:101], v[10:13], 0
	ds_read_b128 v[98:101], v82 offset:8192
	s_add_i32 m0, s10, 0x0
	s_nop 0
	global_load_lds_dwordx4 v124, s[64:65]
	s_waitcnt lgkmcnt(3)
	v_mfma_f32_32x32x16_bf16 v[138:153], v[102:105], v[14:17], v[138:153]
	ds_read_b128 v[102:105], v83 offset:8192
	s_add_i32 m0, s10, 0x2000
	s_nop 0
	global_load_lds_dwordx4 v124, s[66:67]
	s_waitcnt lgkmcnt(3)
	v_mfma_f32_32x32x16_bf16 v[138:153], v[106:109], v[2:5], v[138:153]
	ds_read_b128 v[106:109], v84 offset:8192
	s_add_i32 m0, s10, 0x4000
	s_nop 0
	global_load_lds_dwordx4 v124, s[68:69]
	s_waitcnt lgkmcnt(3)
	v_mfma_f32_32x32x16_bf16 v[138:153], v[110:113], v[6:9], v[138:153]
	ds_read_b128 v[110:113], v85 offset:8192
	s_add_i32 m0, s10, 0x6000
	s_nop 0
	global_load_lds_dwordx4 v124, s[70:71]
	v_add_u32_e32 v124, s36, v124
	s_waitcnt lgkmcnt(3)
	v_mfma_f32_32x32x16_bf16 v[154:169], v[98:101], v[10:13], 0
	ds_read_b128 v[98:101], v82 offset:16384
	s_add_i32 m0, s6, 0x0
	s_nop 0
	global_load_lds_dwordx4 v125, s[72:73]
	ds_read_b128 v[128:131], v86 offset:0
	ds_read_b128 v[184:187], v86 offset:8192
	v_exp_f32_e32 v138, v138
	v_exp_f32_e32 v139, v139
	v_exp_f32_e32 v140, v140
	v_exp_f32_e32 v141, v141
	v_exp_f32_e32 v142, v142
	v_exp_f32_e32 v143, v143
	s_waitcnt lgkmcnt(5)
	v_mfma_f32_32x32x16_bf16 v[154:169], v[102:105], v[14:17], v[154:169]
	ds_read_b128 v[102:105], v83 offset:16384
	s_add_i32 m0, s6, 0x2000
	s_nop 0
	global_load_lds_dwordx4 v125, s[74:75]
	ds_read_b128 v[188:191], v86 offset:16384
	ds_read_b128 v[192:195], v86 offset:24576
	v_exp_f32_e32 v144, v144
	v_exp_f32_e32 v145, v145
	v_add_f32_e32 v122, v138, v122
	v_add_f32_e32 v122, v139, v122
	v_add_f32_e32 v122, v140, v122
	v_add_f32_e32 v122, v141, v122
	v_add_f32_e32 v122, v142, v122
	v_add_f32_e32 v122, v143, v122
	v_add_f32_e32 v122, v144, v122
	v_add_f32_e32 v122, v145, v122
	v_cvt_pk_bf16_f32 v114, v138, v139
	v_cvt_pk_bf16_f32 v115, v140, v141
	v_cvt_pk_bf16_f32 v116, v142, v143
	v_cvt_pk_bf16_f32 v117, v144, v145
	s_waitcnt lgkmcnt(7)
	v_mfma_f32_32x32x16_bf16 v[154:169], v[106:109], v[2:5], v[154:169]
	ds_read_b128 v[106:109], v84 offset:16384
	s_add_i32 m0, s6, 0x4000
	s_nop 0
	global_load_lds_dwordx4 v125, s[76:77]
	ds_read_b128 v[196:199], v87 offset:0
	v_exp_f32_e32 v146, v146
	v_exp_f32_e32 v147, v147
	s_waitcnt lgkmcnt(6)
	v_mfma_f32_32x32x16_bf16 v[18:33], v[128:131], v[114:117], v[18:33]
	s_add_i32 m0, s6, 0x6000
	s_nop 0
	global_load_lds_dwordx4 v125, s[78:79]
	v_add_u32_e32 v125, s38, v125
	ds_read_b128 v[216:219], v87 offset:8192
	v_exp_f32_e32 v148, v148
	v_exp_f32_e32 v149, v149
	s_waitcnt lgkmcnt(6)
	v_mfma_f32_32x32x16_bf16 v[34:49], v[184:187], v[114:117], v[34:49]
	v_exp_f32_e32 v150, v150
	v_exp_f32_e32 v151, v151
	v_mfma_f32_32x32x16_bf16 v[154:169], v[110:113], v[6:9], v[154:169]
	ds_read_b128 v[110:113], v85 offset:16384
	ds_read_b128 v[200:203], v87 offset:16384
	v_exp_f32_e32 v152, v152
	v_exp_f32_e32 v153, v153
	s_waitcnt lgkmcnt(6)
	v_mfma_f32_32x32x16_bf16 v[50:65], v[188:191], v[114:117], v[50:65]
	ds_read_b128 v[204:207], v87 offset:24576
	v_add_f32_e32 v122, v146, v122
	v_add_f32_e32 v122, v147, v122
	v_add_f32_e32 v122, v148, v122
	v_add_f32_e32 v122, v149, v122
	s_waitcnt lgkmcnt(6)
	v_mfma_f32_32x32x16_bf16 v[66:81], v[192:195], v[114:117], v[66:81]
	v_add_f32_e32 v122, v150, v122
	v_add_f32_e32 v122, v151, v122
	v_add_f32_e32 v122, v152, v122
	v_add_f32_e32 v122, v153, v122
	v_cvt_pk_bf16_f32 v118, v146, v147
	v_cvt_pk_bf16_f32 v119, v148, v149
	v_cvt_pk_bf16_f32 v120, v150, v151
	v_cvt_pk_bf16_f32 v121, v152, v153
	v_mfma_f32_32x32x16_bf16 v[138:153], v[98:101], v[10:13], 0
	ds_read_b128 v[98:101], v82 offset:24576
	ds_read_b128 v[128:131], v88 offset:0
	v_exp_f32_e32 v154, v154
	v_exp_f32_e32 v155, v155
	s_waitcnt lgkmcnt(6)
	v_mfma_f32_32x32x16_bf16 v[18:33], v[196:199], v[118:121], v[18:33]
	ds_read_b128 v[184:187], v88 offset:8192
	v_exp_f32_e32 v156, v156
	v_exp_f32_e32 v157, v157
	s_waitcnt lgkmcnt(6)
	v_mfma_f32_32x32x16_bf16 v[34:49], v[216:219], v[118:121], v[34:49]
	v_exp_f32_e32 v158, v158
	v_exp_f32_e32 v159, v159
	v_mfma_f32_32x32x16_bf16 v[138:153], v[102:105], v[14:17], v[138:153]
	ds_read_b128 v[102:105], v83 offset:24576
	ds_read_b128 v[188:191], v88 offset:16384
	v_exp_f32_e32 v160, v160
	v_exp_f32_e32 v161, v161
	s_waitcnt lgkmcnt(6)
	v_mfma_f32_32x32x16_bf16 v[50:65], v[200:203], v[118:121], v[50:65]
	ds_read_b128 v[192:195], v88 offset:24576
	v_add_f32_e32 v122, v154, v122
	v_add_f32_e32 v122, v155, v122
	v_add_f32_e32 v122, v156, v122
	v_add_f32_e32 v122, v157, v122
	s_waitcnt lgkmcnt(6)
	v_mfma_f32_32x32x16_bf16 v[66:81], v[204:207], v[118:121], v[66:81]
	v_add_f32_e32 v122, v158, v122
	v_add_f32_e32 v122, v159, v122
	v_add_f32_e32 v122, v160, v122
	v_add_f32_e32 v122, v161, v122
	v_cvt_pk_bf16_f32 v114, v154, v155
	v_cvt_pk_bf16_f32 v115, v156, v157
	v_cvt_pk_bf16_f32 v116, v158, v159
	v_cvt_pk_bf16_f32 v117, v160, v161
	v_mfma_f32_32x32x16_bf16 v[138:153], v[106:109], v[2:5], v[138:153]
	ds_read_b128 v[106:109], v84 offset:24576
	ds_read_b128 v[196:199], v89 offset:0
	v_exp_f32_e32 v162, v162
	v_exp_f32_e32 v163, v163
	s_waitcnt lgkmcnt(6)
	v_mfma_f32_32x32x16_bf16 v[18:33], v[128:131], v[114:117], v[18:33]
	ds_read_b128 v[216:219], v89 offset:8192
	v_exp_f32_e32 v164, v164
	v_exp_f32_e32 v165, v165
	s_waitcnt lgkmcnt(6)
	v_mfma_f32_32x32x16_bf16 v[34:49], v[184:187], v[114:117], v[34:49]
	v_exp_f32_e32 v166, v166
	v_exp_f32_e32 v167, v167
	v_mfma_f32_32x32x16_bf16 v[138:153], v[110:113], v[6:9], v[138:153]
	ds_read_b128 v[110:113], v85 offset:24576
	ds_read_b128 v[200:203], v89 offset:16384
	v_exp_f32_e32 v168, v168
	v_exp_f32_e32 v169, v169
	s_waitcnt lgkmcnt(6)
	v_mfma_f32_32x32x16_bf16 v[50:65], v[188:191], v[114:117], v[50:65]
	ds_read_b128 v[204:207], v89 offset:24576
	v_add_f32_e32 v122, v162, v122
	v_add_f32_e32 v122, v163, v122
	v_add_f32_e32 v122, v164, v122
	v_add_f32_e32 v122, v165, v122
	s_waitcnt lgkmcnt(6)
	v_mfma_f32_32x32x16_bf16 v[66:81], v[192:195], v[114:117], v[66:81]
	v_add_f32_e32 v122, v166, v122
	v_add_f32_e32 v122, v167, v122
	v_add_f32_e32 v122, v168, v122
	v_add_f32_e32 v122, v169, v122
	v_cvt_pk_bf16_f32 v118, v162, v163
	v_cvt_pk_bf16_f32 v119, v164, v165
	v_cvt_pk_bf16_f32 v120, v166, v167
	v_cvt_pk_bf16_f32 v121, v168, v169
	v_mfma_f32_32x32x16_bf16 v[154:169], v[98:101], v[10:13], 0
	ds_read_b128 v[128:131], v90 offset:0
	v_exp_f32_e32 v138, v138
	v_exp_f32_e32 v139, v139
	s_waitcnt lgkmcnt(5)
	v_mfma_f32_32x32x16_bf16 v[18:33], v[196:199], v[118:121], v[18:33]
	ds_read_b128 v[184:187], v90 offset:8192
	v_exp_f32_e32 v140, v140
	v_exp_f32_e32 v141, v141
	s_waitcnt lgkmcnt(5)
	v_mfma_f32_32x32x16_bf16 v[34:49], v[216:219], v[118:121], v[34:49]
	v_exp_f32_e32 v142, v142
	v_exp_f32_e32 v143, v143
	v_mfma_f32_32x32x16_bf16 v[154:169], v[102:105], v[14:17], v[154:169]
	ds_read_b128 v[188:191], v90 offset:16384
	v_exp_f32_e32 v144, v144
	v_exp_f32_e32 v145, v145
	s_waitcnt lgkmcnt(4)
	v_mfma_f32_32x32x16_bf16 v[50:65], v[200:203], v[118:121], v[50:65]
	ds_read_b128 v[192:195], v90 offset:24576
	v_add_f32_e32 v122, v138, v122
	v_add_f32_e32 v122, v139, v122
	v_add_f32_e32 v122, v140, v122
	v_add_f32_e32 v122, v141, v122
	s_waitcnt lgkmcnt(4)
	v_mfma_f32_32x32x16_bf16 v[66:81], v[204:207], v[118:121], v[66:81]
	v_add_f32_e32 v122, v142, v122
	v_add_f32_e32 v122, v143, v122
	v_add_f32_e32 v122, v144, v122
	v_add_f32_e32 v122, v145, v122
	v_cvt_pk_bf16_f32 v114, v138, v139
	v_cvt_pk_bf16_f32 v115, v140, v141
	v_cvt_pk_bf16_f32 v116, v142, v143
	v_cvt_pk_bf16_f32 v117, v144, v145
	v_mfma_f32_32x32x16_bf16 v[154:169], v[106:109], v[2:5], v[154:169]
	ds_read_b128 v[196:199], v91 offset:0
	v_exp_f32_e32 v146, v146
	v_exp_f32_e32 v147, v147
	s_waitcnt lgkmcnt(4)
	v_mfma_f32_32x32x16_bf16 v[18:33], v[128:131], v[114:117], v[18:33]
	ds_read_b128 v[216:219], v91 offset:8192
	v_exp_f32_e32 v148, v148
	v_exp_f32_e32 v149, v149
	s_waitcnt lgkmcnt(4)
	v_mfma_f32_32x32x16_bf16 v[34:49], v[184:187], v[114:117], v[34:49]
	v_exp_f32_e32 v150, v150
	v_exp_f32_e32 v151, v151
	v_mfma_f32_32x32x16_bf16 v[154:169], v[110:113], v[6:9], v[154:169]
	ds_read_b128 v[200:203], v91 offset:16384
	v_exp_f32_e32 v152, v152
	v_exp_f32_e32 v153, v153
	s_waitcnt lgkmcnt(4)
	v_mfma_f32_32x32x16_bf16 v[50:65], v[188:191], v[114:117], v[50:65]
	ds_read_b128 v[204:207], v91 offset:24576
	v_add_f32_e32 v122, v146, v122
	v_add_f32_e32 v122, v147, v122
	v_add_f32_e32 v122, v148, v122
	v_add_f32_e32 v122, v149, v122
	s_waitcnt lgkmcnt(4)
	v_mfma_f32_32x32x16_bf16 v[66:81], v[192:195], v[114:117], v[66:81]
	v_add_f32_e32 v122, v150, v122
	v_add_f32_e32 v122, v151, v122
	v_add_f32_e32 v122, v152, v122
	v_add_f32_e32 v122, v153, v122
	v_cvt_pk_bf16_f32 v118, v146, v147
	v_cvt_pk_bf16_f32 v119, v148, v149
	v_cvt_pk_bf16_f32 v120, v150, v151
	v_cvt_pk_bf16_f32 v121, v152, v153
	s_waitcnt lgkmcnt(3)
	s_nop 0
	v_mfma_f32_32x32x16_bf16 v[18:33], v[196:199], v[118:121], v[18:33]
	ds_read_b128 v[128:131], v92 offset:0
	v_exp_f32_e32 v154, v154
	v_exp_f32_e32 v155, v155
	v_exp_f32_e32 v156, v156
	s_waitcnt lgkmcnt(3)
	v_mfma_f32_32x32x16_bf16 v[34:49], v[216:219], v[118:121], v[34:49]
	ds_read_b128 v[184:187], v92 offset:8192
	v_exp_f32_e32 v157, v157
	v_exp_f32_e32 v158, v158
	v_exp_f32_e32 v159, v159
	v_exp_f32_e32 v160, v160
	s_waitcnt lgkmcnt(3)
	v_mfma_f32_32x32x16_bf16 v[50:65], v[200:203], v[118:121], v[50:65]
	ds_read_b128 v[188:191], v92 offset:16384
	v_exp_f32_e32 v161, v161
	v_add_f32_e32 v122, v154, v122
	v_add_f32_e32 v122, v155, v122
	v_add_f32_e32 v122, v156, v122
	v_add_f32_e32 v122, v157, v122
	v_add_f32_e32 v122, v158, v122
	s_waitcnt lgkmcnt(3)
	v_mfma_f32_32x32x16_bf16 v[66:81], v[204:207], v[118:121], v[66:81]
	ds_read_b128 v[192:195], v92 offset:24576
	v_add_f32_e32 v122, v159, v122
	v_add_f32_e32 v122, v160, v122
	v_add_f32_e32 v122, v161, v122
	v_xor_b32_e32 v82, 0x8000, v82
	v_xor_b32_e32 v83, 0x8000, v83
	v_xor_b32_e32 v84, 0x8000, v84
	v_xor_b32_e32 v85, 0x8000, v85
	v_cvt_pk_bf16_f32 v114, v154, v155
	v_cvt_pk_bf16_f32 v115, v156, v157
	v_cvt_pk_bf16_f32 v116, v158, v159
	v_cvt_pk_bf16_f32 v117, v160, v161
	s_waitcnt lgkmcnt(3)
	s_nop 0
	v_mfma_f32_32x32x16_bf16 v[18:33], v[128:131], v[114:117], v[18:33]
	ds_read_b128 v[196:199], v93 offset:0
	v_exp_f32_e32 v162, v162
	v_exp_f32_e32 v163, v163
	v_exp_f32_e32 v164, v164
	s_waitcnt lgkmcnt(3)
	v_mfma_f32_32x32x16_bf16 v[34:49], v[184:187], v[114:117], v[34:49]
	ds_read_b128 v[216:219], v93 offset:8192
	v_exp_f32_e32 v165, v165
	v_exp_f32_e32 v166, v166
	v_exp_f32_e32 v167, v167
	s_waitcnt lgkmcnt(3)
	v_mfma_f32_32x32x16_bf16 v[50:65], v[188:191], v[114:117], v[50:65]
	ds_read_b128 v[200:203], v93 offset:16384
	v_exp_f32_e32 v168, v168
	v_exp_f32_e32 v169, v169
	v_add_f32_e32 v122, v162, v122
	v_add_f32_e32 v122, v163, v122
	s_waitcnt lgkmcnt(3)
	v_mfma_f32_32x32x16_bf16 v[66:81], v[192:195], v[114:117], v[66:81]
	ds_read_b128 v[204:207], v93 offset:24576
	v_add_f32_e32 v122, v164, v122
	v_add_f32_e32 v122, v165, v122
	v_add_f32_e32 v122, v166, v122
	v_add_f32_e32 v122, v167, v122
	v_add_f32_e32 v122, v168, v122
	v_add_f32_e32 v122, v169, v122
	v_cvt_pk_bf16_f32 v118, v162, v163
	v_cvt_pk_bf16_f32 v119, v164, v165
	v_cvt_pk_bf16_f32 v120, v166, v167
	v_cvt_pk_bf16_f32 v121, v168, v169
	s_waitcnt lgkmcnt(3)
	s_nop 0
	v_mfma_f32_32x32x16_bf16 v[18:33], v[196:199], v[118:121], v[18:33]
	v_xor_b32_e32 v86, 0x8000, v86
	v_xor_b32_e32 v87, 0x8000, v87
	s_waitcnt lgkmcnt(2)
	v_mfma_f32_32x32x16_bf16 v[34:49], v[216:219], v[118:121], v[34:49]
	v_xor_b32_e32 v88, 0x8000, v88
	v_xor_b32_e32 v89, 0x8000, v89
	s_waitcnt lgkmcnt(1)
	v_mfma_f32_32x32x16_bf16 v[50:65], v[200:203], v[118:121], v[50:65]
	v_xor_b32_e32 v90, 0x8000, v90
	v_xor_b32_e32 v91, 0x8000, v91
	s_waitcnt lgkmcnt(0)
	v_mfma_f32_32x32x16_bf16 v[66:81], v[204:207], v[118:121], v[66:81]
	v_xor_b32_e32 v92, 0x8000, v92
	v_xor_b32_e32 v93, 0x8000, v93
	s_waitcnt vmcnt(0)
	s_waitcnt lgkmcnt(0)
	s_barrier
	s_add_i32 s15, s15, 1
	s_cmp_eq_u32 s15, 33
	s_cbranch_scc0 .Lattn_nf_loop
	ds_read_b128 v[98:101], v82 offset:0
	ds_read_b128 v[102:105], v83 offset:0
	ds_read_b128 v[106:109], v84 offset:0
	ds_read_b128 v[110:113], v85 offset:0
	s_waitcnt lgkmcnt(3)
	v_mfma_f32_32x32x16_bf16 v[138:153], v[98:101], v[10:13], 0
	ds_read_b128 v[98:101], v82 offset:8192
	s_waitcnt lgkmcnt(3)
	v_mfma_f32_32x32x16_bf16 v[138:153], v[102:105], v[14:17], v[138:153]
	ds_read_b128 v[102:105], v83 offset:8192
	s_waitcnt lgkmcnt(3)
	v_mfma_f32_32x32x16_bf16 v[138:153], v[106:109], v[2:5], v[138:153]
	ds_read_b128 v[106:109], v84 offset:8192
	s_waitcnt lgkmcnt(3)
	v_mfma_f32_32x32x16_bf16 v[138:153], v[110:113], v[6:9], v[138:153]
	ds_read_b128 v[110:113], v85 offset:8192
	s_waitcnt lgkmcnt(3)
	v_mfma_f32_32x32x16_bf16 v[154:169], v[98:101], v[10:13], 0
	ds_read_b128 v[98:101], v82 offset:16384
	ds_read_b128 v[128:131], v86 offset:0
	ds_read_b128 v[184:187], v86 offset:8192
	s_nop 5
	v_exp_f32_e32 v138, v138
	v_exp_f32_e32 v139, v139
	v_exp_f32_e32 v140, v140
	v_exp_f32_e32 v141, v141
	v_exp_f32_e32 v142, v142
	v_exp_f32_e32 v143, v143
	s_waitcnt lgkmcnt(5)
	v_mfma_f32_32x32x16_bf16 v[154:169], v[102:105], v[14:17], v[154:169]
	ds_read_b128 v[102:105], v83 offset:16384
	ds_read_b128 v[188:191], v86 offset:16384
	ds_read_b128 v[192:195], v86 offset:24576
	v_exp_f32_e32 v144, v144
	v_exp_f32_e32 v145, v145
	v_add_f32_e32 v122, v138, v122
	v_add_f32_e32 v122, v139, v122
	v_add_f32_e32 v122, v140, v122
	v_add_f32_e32 v122, v141, v122
	v_add_f32_e32 v122, v142, v122
	v_add_f32_e32 v122, v143, v122
	v_add_f32_e32 v122, v144, v122
	v_add_f32_e32 v122, v145, v122
	v_cvt_pk_bf16_f32 v114, v138, v139
	v_cvt_pk_bf16_f32 v115, v140, v141
	v_cvt_pk_bf16_f32 v116, v142, v143
	v_cvt_pk_bf16_f32 v117, v144, v145
	s_waitcnt lgkmcnt(7)
	v_mfma_f32_32x32x16_bf16 v[154:169], v[106:109], v[2:5], v[154:169]
	ds_read_b128 v[106:109], v84 offset:16384
	ds_read_b128 v[196:199], v87 offset:0
	v_exp_f32_e32 v146, v146
	v_exp_f32_e32 v147, v147
	s_waitcnt lgkmcnt(6)
	v_mfma_f32_32x32x16_bf16 v[18:33], v[128:131], v[114:117], v[18:33]
	ds_read_b128 v[216:219], v87 offset:8192
	v_exp_f32_e32 v148, v148
	v_exp_f32_e32 v149, v149
	s_waitcnt lgkmcnt(6)
	v_mfma_f32_32x32x16_bf16 v[34:49], v[184:187], v[114:117], v[34:49]
	v_exp_f32_e32 v150, v150
	v_exp_f32_e32 v151, v151
	v_mfma_f32_32x32x16_bf16 v[154:169], v[110:113], v[6:9], v[154:169]
	ds_read_b128 v[110:113], v85 offset:16384
	ds_read_b128 v[200:203], v87 offset:16384
	v_exp_f32_e32 v152, v152
	v_exp_f32_e32 v153, v153
	s_waitcnt lgkmcnt(6)
	v_mfma_f32_32x32x16_bf16 v[50:65], v[188:191], v[114:117], v[50:65]
	ds_read_b128 v[204:207], v87 offset:24576
	v_add_f32_e32 v122, v146, v122
	v_add_f32_e32 v122, v147, v122
	v_add_f32_e32 v122, v148, v122
	v_add_f32_e32 v122, v149, v122
	s_waitcnt lgkmcnt(6)
	v_mfma_f32_32x32x16_bf16 v[66:81], v[192:195], v[114:117], v[66:81]
	v_add_f32_e32 v122, v150, v122
	v_add_f32_e32 v122, v151, v122
	v_add_f32_e32 v122, v152, v122
	v_add_f32_e32 v122, v153, v122
	v_cvt_pk_bf16_f32 v118, v146, v147
	v_cvt_pk_bf16_f32 v119, v148, v149
	v_cvt_pk_bf16_f32 v120, v150, v151
	v_cvt_pk_bf16_f32 v121, v152, v153
	v_mfma_f32_32x32x16_bf16 v[138:153], v[98:101], v[10:13], 0
	ds_read_b128 v[98:101], v82 offset:24576
	ds_read_b128 v[128:131], v88 offset:0
	v_exp_f32_e32 v154, v154
	v_exp_f32_e32 v155, v155
	s_waitcnt lgkmcnt(6)
	v_mfma_f32_32x32x16_bf16 v[18:33], v[196:199], v[118:121], v[18:33]
	ds_read_b128 v[184:187], v88 offset:8192
	v_exp_f32_e32 v156, v156
	v_exp_f32_e32 v157, v157
	s_waitcnt lgkmcnt(6)
	v_mfma_f32_32x32x16_bf16 v[34:49], v[216:219], v[118:121], v[34:49]
	v_exp_f32_e32 v158, v158
	v_exp_f32_e32 v159, v159
	v_mfma_f32_32x32x16_bf16 v[138:153], v[102:105], v[14:17], v[138:153]
	ds_read_b128 v[102:105], v83 offset:24576
	ds_read_b128 v[188:191], v88 offset:16384
	v_exp_f32_e32 v160, v160
	v_exp_f32_e32 v161, v161
	s_waitcnt lgkmcnt(6)
	v_mfma_f32_32x32x16_bf16 v[50:65], v[200:203], v[118:121], v[50:65]
	ds_read_b128 v[192:195], v88 offset:24576
	v_add_f32_e32 v122, v154, v122
	v_add_f32_e32 v122, v155, v122
	v_add_f32_e32 v122, v156, v122
	v_add_f32_e32 v122, v157, v122
	s_waitcnt lgkmcnt(6)
	v_mfma_f32_32x32x16_bf16 v[66:81], v[204:207], v[118:121], v[66:81]
	v_add_f32_e32 v122, v158, v122
	v_add_f32_e32 v122, v159, v122
	v_add_f32_e32 v122, v160, v122
	v_add_f32_e32 v122, v161, v122
	v_cvt_pk_bf16_f32 v114, v154, v155
	v_cvt_pk_bf16_f32 v115, v156, v157
	v_cvt_pk_bf16_f32 v116, v158, v159
	v_cvt_pk_bf16_f32 v117, v160, v161
	v_mfma_f32_32x32x16_bf16 v[138:153], v[106:109], v[2:5], v[138:153]
	ds_read_b128 v[106:109], v84 offset:24576
	ds_read_b128 v[196:199], v89 offset:0
	v_exp_f32_e32 v162, v162
	v_exp_f32_e32 v163, v163
	s_waitcnt lgkmcnt(6)
	v_mfma_f32_32x32x16_bf16 v[18:33], v[128:131], v[114:117], v[18:33]
	ds_read_b128 v[216:219], v89 offset:8192
	v_exp_f32_e32 v164, v164
	v_exp_f32_e32 v165, v165
	s_waitcnt lgkmcnt(6)
	v_mfma_f32_32x32x16_bf16 v[34:49], v[184:187], v[114:117], v[34:49]
	v_exp_f32_e32 v166, v166
	v_exp_f32_e32 v167, v167
	v_mfma_f32_32x32x16_bf16 v[138:153], v[110:113], v[6:9], v[138:153]
	ds_read_b128 v[110:113], v85 offset:24576
	ds_read_b128 v[200:203], v89 offset:16384
	v_exp_f32_e32 v168, v168
	v_exp_f32_e32 v169, v169
	s_waitcnt lgkmcnt(6)
	v_mfma_f32_32x32x16_bf16 v[50:65], v[188:191], v[114:117], v[50:65]
	ds_read_b128 v[204:207], v89 offset:24576
	v_add_f32_e32 v122, v162, v122
	v_add_f32_e32 v122, v163, v122
	v_add_f32_e32 v122, v164, v122
	v_add_f32_e32 v122, v165, v122
	s_waitcnt lgkmcnt(6)
	v_mfma_f32_32x32x16_bf16 v[66:81], v[192:195], v[114:117], v[66:81]
	v_add_f32_e32 v122, v166, v122
	v_add_f32_e32 v122, v167, v122
	v_add_f32_e32 v122, v168, v122
	v_add_f32_e32 v122, v169, v122
	v_cvt_pk_bf16_f32 v118, v162, v163
	v_cvt_pk_bf16_f32 v119, v164, v165
	v_cvt_pk_bf16_f32 v120, v166, v167
	v_cvt_pk_bf16_f32 v121, v168, v169
	v_mfma_f32_32x32x16_bf16 v[154:169], v[98:101], v[10:13], 0
	ds_read_b128 v[128:131], v90 offset:0
	v_exp_f32_e32 v138, v138
	v_exp_f32_e32 v139, v139
	s_waitcnt lgkmcnt(5)
	v_mfma_f32_32x32x16_bf16 v[18:33], v[196:199], v[118:121], v[18:33]
	ds_read_b128 v[184:187], v90 offset:8192
	v_exp_f32_e32 v140, v140
	v_exp_f32_e32 v141, v141
	s_waitcnt lgkmcnt(5)
	v_mfma_f32_32x32x16_bf16 v[34:49], v[216:219], v[118:121], v[34:49]
	v_exp_f32_e32 v142, v142
	v_exp_f32_e32 v143, v143
	v_mfma_f32_32x32x16_bf16 v[154:169], v[102:105], v[14:17], v[154:169]
	ds_read_b128 v[188:191], v90 offset:16384
	v_exp_f32_e32 v144, v144
	v_exp_f32_e32 v145, v145
	s_waitcnt lgkmcnt(4)
	v_mfma_f32_32x32x16_bf16 v[50:65], v[200:203], v[118:121], v[50:65]
	ds_read_b128 v[192:195], v90 offset:24576
	v_add_f32_e32 v122, v138, v122
	v_add_f32_e32 v122, v139, v122
	v_add_f32_e32 v122, v140, v122
	v_add_f32_e32 v122, v141, v122
	s_waitcnt lgkmcnt(4)
	v_mfma_f32_32x32x16_bf16 v[66:81], v[204:207], v[118:121], v[66:81]
	v_add_f32_e32 v122, v142, v122
	v_add_f32_e32 v122, v143, v122
	v_add_f32_e32 v122, v144, v122
	v_add_f32_e32 v122, v145, v122
	v_cvt_pk_bf16_f32 v114, v138, v139
	v_cvt_pk_bf16_f32 v115, v140, v141
	v_cvt_pk_bf16_f32 v116, v142, v143
	v_cvt_pk_bf16_f32 v117, v144, v145
	v_mfma_f32_32x32x16_bf16 v[154:169], v[106:109], v[2:5], v[154:169]
	ds_read_b128 v[196:199], v91 offset:0
	v_exp_f32_e32 v146, v146
	v_exp_f32_e32 v147, v147
	s_waitcnt lgkmcnt(4)
	v_mfma_f32_32x32x16_bf16 v[18:33], v[128:131], v[114:117], v[18:33]
	ds_read_b128 v[216:219], v91 offset:8192
	v_exp_f32_e32 v148, v148
	v_exp_f32_e32 v149, v149
	s_waitcnt lgkmcnt(4)
	v_mfma_f32_32x32x16_bf16 v[34:49], v[184:187], v[114:117], v[34:49]
	v_exp_f32_e32 v150, v150
	v_exp_f32_e32 v151, v151
	v_mfma_f32_32x32x16_bf16 v[154:169], v[110:113], v[6:9], v[154:169]
	ds_read_b128 v[200:203], v91 offset:16384
	v_exp_f32_e32 v152, v152
	v_exp_f32_e32 v153, v153
	s_waitcnt lgkmcnt(4)
	v_mfma_f32_32x32x16_bf16 v[50:65], v[188:191], v[114:117], v[50:65]
	ds_read_b128 v[204:207], v91 offset:24576
	v_add_f32_e32 v122, v146, v122
	v_add_f32_e32 v122, v147, v122
	v_add_f32_e32 v122, v148, v122
	v_add_f32_e32 v122, v149, v122
	s_waitcnt lgkmcnt(4)
	v_mfma_f32_32x32x16_bf16 v[66:81], v[192:195], v[114:117], v[66:81]
	v_add_f32_e32 v122, v150, v122
	v_add_f32_e32 v122, v151, v122
	v_add_f32_e32 v122, v152, v122
	v_add_f32_e32 v122, v153, v122
	v_cvt_pk_bf16_f32 v118, v146, v147
	v_cvt_pk_bf16_f32 v119, v148, v149
	v_cvt_pk_bf16_f32 v120, v150, v151
	v_cvt_pk_bf16_f32 v121, v152, v153
	s_waitcnt lgkmcnt(3)
	s_nop 0
	v_mfma_f32_32x32x16_bf16 v[18:33], v[196:199], v[118:121], v[18:33]
	ds_read_b128 v[128:131], v92 offset:0
	v_exp_f32_e32 v154, v154
	v_exp_f32_e32 v155, v155
	v_exp_f32_e32 v156, v156
	s_waitcnt lgkmcnt(3)
	v_mfma_f32_32x32x16_bf16 v[34:49], v[216:219], v[118:121], v[34:49]
	ds_read_b128 v[184:187], v92 offset:8192
	v_exp_f32_e32 v157, v157
	v_exp_f32_e32 v158, v158
	v_exp_f32_e32 v159, v159
	s_waitcnt lgkmcnt(3)
	v_mfma_f32_32x32x16_bf16 v[50:65], v[200:203], v[118:121], v[50:65]
	ds_read_b128 v[188:191], v92 offset:16384
	v_exp_f32_e32 v160, v160
	v_exp_f32_e32 v161, v161
	v_add_f32_e32 v122, v154, v122
	v_add_f32_e32 v122, v155, v122
	s_waitcnt lgkmcnt(3)
	v_mfma_f32_32x32x16_bf16 v[66:81], v[204:207], v[118:121], v[66:81]
	ds_read_b128 v[192:195], v92 offset:24576
	v_add_f32_e32 v122, v156, v122
	v_add_f32_e32 v122, v157, v122
	v_add_f32_e32 v122, v158, v122
	v_add_f32_e32 v122, v159, v122
	v_add_f32_e32 v122, v160, v122
	v_add_f32_e32 v122, v161, v122
	v_cvt_pk_bf16_f32 v114, v154, v155
	v_cvt_pk_bf16_f32 v115, v156, v157
	v_cvt_pk_bf16_f32 v116, v158, v159
	v_cvt_pk_bf16_f32 v117, v160, v161
	s_waitcnt lgkmcnt(3)
	s_nop 0
	v_mfma_f32_32x32x16_bf16 v[18:33], v[128:131], v[114:117], v[18:33]
	ds_read_b128 v[196:199], v93 offset:0
	v_exp_f32_e32 v162, v162
	v_exp_f32_e32 v163, v163
	v_exp_f32_e32 v164, v164
	s_waitcnt lgkmcnt(3)
	v_mfma_f32_32x32x16_bf16 v[34:49], v[184:187], v[114:117], v[34:49]
	ds_read_b128 v[216:219], v93 offset:8192
	v_exp_f32_e32 v165, v165
	v_exp_f32_e32 v166, v166
	v_exp_f32_e32 v167, v167
	s_waitcnt lgkmcnt(3)
	v_mfma_f32_32x32x16_bf16 v[50:65], v[188:191], v[114:117], v[50:65]
	ds_read_b128 v[200:203], v93 offset:16384
	v_exp_f32_e32 v168, v168
	v_exp_f32_e32 v169, v169
	v_add_f32_e32 v122, v162, v122
	v_add_f32_e32 v122, v163, v122
	s_waitcnt lgkmcnt(3)
	v_mfma_f32_32x32x16_bf16 v[66:81], v[192:195], v[114:117], v[66:81]
	ds_read_b128 v[204:207], v93 offset:24576
	v_add_f32_e32 v122, v164, v122
	v_add_f32_e32 v122, v165, v122
	v_add_f32_e32 v122, v166, v122
	v_add_f32_e32 v122, v167, v122
	v_add_f32_e32 v122, v168, v122
	v_add_f32_e32 v122, v169, v122
	v_cvt_pk_bf16_f32 v118, v162, v163
	v_cvt_pk_bf16_f32 v119, v164, v165
	v_cvt_pk_bf16_f32 v120, v166, v167
	v_cvt_pk_bf16_f32 v121, v168, v169
	s_waitcnt lgkmcnt(3)
	s_nop 0
	v_mfma_f32_32x32x16_bf16 v[18:33], v[196:199], v[118:121], v[18:33]
	s_waitcnt lgkmcnt(2)
	v_mfma_f32_32x32x16_bf16 v[34:49], v[216:219], v[118:121], v[34:49]
	s_waitcnt lgkmcnt(1)
	v_mfma_f32_32x32x16_bf16 v[50:65], v[200:203], v[118:121], v[50:65]
	s_waitcnt lgkmcnt(0)
	v_mfma_f32_32x32x16_bf16 v[66:81], v[204:207], v[118:121], v[66:81]
	s_waitcnt vmcnt(0)
	s_waitcnt lgkmcnt(0)
	s_barrier
	v_readlane_b32 s64, v175, 0
	v_readlane_b32 s65, v175, 1
	v_readlane_b32 s66, v175, 2
	v_readlane_b32 s67, v175, 3
	v_readlane_b32 s68, v175, 4
	v_readlane_b32 s69, v175, 5
	v_readlane_b32 s70, v175, 6
	v_readlane_b32 s71, v175, 7
	v_readlane_b32 s72, v175, 8
	v_readlane_b32 s73, v175, 9
	v_readlane_b32 s74, v175, 10
	v_readlane_b32 s75, v175, 11
	v_readlane_b32 s76, v175, 12
	v_readlane_b32 s77, v175, 13
	v_readlane_b32 s78, v175, 14
	v_readlane_b32 s79, v175, 15
	s_nop 4
	s_mov_b32 s10, 0x3fb8aa3b
	s_mov_b32 s11, 0xc2ce8ed0
	s_mov_b32 s6, 0x42b17218
	v_cmp_eq_u32_e64 s[40:41], 0, v179
	s_lshl_b32 s30, s14, 1
	v_lshlrev_b32_e32 v196, 3, v178
	v_mov_b32_e32 v197, 0
	v_lshlrev_b32_e32 v198, 4, v179
	v_or3_b32 v198, v198, v177, v180
	v_ashrrev_i32_e32 v199, 31, v198
	v_lshlrev_b64 v[198:199], 11, v[198:199]
	s_mov_b64 s[100:101], 0x18a10000
	v_lshl_add_u64 v[198:199], s[42:43], 0, v[198:199]
	v_lshl_add_u64 v[198:199], v[198:199], 0, s[30:31]
	v_lshl_add_u64 v[198:199], v[198:199], 0, v[196:197]
	v_lshl_add_u64 v[198:199], v[198:199], 0, s[100:101]
	global_load_dwordx2 v[146:147], v[198:199], off
	global_load_dwordx2 v[148:149], v[198:199], off offset:32
	global_load_dwordx2 v[150:151], v[198:199], off offset:64
	global_load_dwordx2 v[152:153], v[198:199], off offset:96
	global_load_dwordx2 v[188:189], v[198:199], off offset:128
	global_load_dwordx2 v[190:191], v[198:199], off offset:160
	global_load_dwordx2 v[192:193], v[198:199], off offset:192
	global_load_dwordx2 v[194:195], v[198:199], off offset:224
	s_mov_b64 s[100:101], exec
	s_and_b64 exec, exec, s[4:5]
	s_cbranch_execz .Lpop_skip
	v_readlane_b32 s14, v255, 22
	v_readlane_b32 s15, v255, 23
	v_mov_b32_e32 v224, 1
	s_nop 4
	global_atomic_add v224, v0, v224, s[14:15] sc0
